# k2 fox: all V-fragment LDS reads issued before the exp block into free registers (as in k9)
# baseline (speedup 1.0000x reference)
.LBB2_57:
	ds_read_b64_tr_b16 v[210:211], v178 offset:39936
	ds_read_b64_tr_b16 v[212:213], v178 offset:42496
	ds_read_b64_tr_b16 v[216:217], v178 offset:42560
	ds_read_b64_tr_b16 v[214:215], v178 offset:40000
	ds_read_b64_tr_b16 v[218:219], v178 offset:45056
	ds_read_b64_tr_b16 v[220:221], v178 offset:47616
	ds_read_b64_tr_b16 v[224:225], v178 offset:47680
	ds_read_b64_tr_b16 v[222:223], v178 offset:45120
	ds_read_b64_tr_b16 v[226:227], v178 offset:50176
	ds_read_b64_tr_b16 v[228:229], v178 offset:52736
	ds_read_b64_tr_b16 v[232:233], v178 offset:52800
	ds_read_b64_tr_b16 v[230:231], v178 offset:50240
	v_exp_f32_e32 v186, v34
	v_exp_f32_e32 v187, v50
	v_exp_f32_e32 v98, v35
	v_exp_f32_e32 v50, v51
	v_exp_f32_e32 v188, v52
	v_add_f32_e32 v51, v187, v186
	v_exp_f32_e32 v52, v53
	v_pk_add_f32 v[34:35], v[50:51], v[98:99]
	v_exp_f32_e32 v51, v36
	v_pk_add_f32 v[100:101], v[34:35], v[34:35] op_sel_hi:[0,1]
	v_exp_f32_e32 v100, v37
	v_add_f32_e32 v53, v188, v51
	v_pk_add_f32 v[34:35], v[52:53], v[100:101]
	s_nop 0
	v_pk_add_f32 v[36:37], v[34:35], v[34:35] op_sel_hi:[0,1]
	v_exp_f32_e32 v53, v38
	v_exp_f32_e32 v101, v54
	v_exp_f32_e32 v36, v39
	v_exp_f32_e32 v54, v55
	v_add_f32_e32 v55, v101, v53
	v_pk_add_f32 v[34:35], v[54:55], v[36:37]
	s_nop 0
	v_pk_add_f32 v[38:39], v[34:35], v[34:35] op_sel_hi:[0,1]
	v_exp_f32_e32 v37, v40
	v_exp_f32_e32 v55, v56
	v_exp_f32_e32 v38, v41
	v_exp_f32_e32 v56, v57
	v_cvt_pk_bf16_f32 v36, v53, v36
	v_add_f32_e32 v57, v55, v37
	v_cvt_pk_bf16_f32 v37, v37, v38
	v_pk_add_f32 v[34:35], v[56:57], v[38:39]
	v_exp_f32_e32 v39, v42
	v_pk_add_f32 v[40:41], v[34:35], v[34:35] op_sel_hi:[0,1]
	v_exp_f32_e32 v57, v58
	v_exp_f32_e32 v40, v43
	v_exp_f32_e32 v58, v59
	v_add_f32_e32 v59, v57, v39
	v_cvt_pk_bf16_f32 v38, v39, v40
	v_pk_add_f32 v[34:35], v[58:59], v[40:41]
	v_exp_f32_e32 v41, v44
	v_pk_add_f32 v[42:43], v[34:35], v[34:35] op_sel_hi:[0,1]
	v_exp_f32_e32 v59, v60
	v_exp_f32_e32 v42, v45
	v_exp_f32_e32 v60, v61
	v_add_f32_e32 v61, v59, v41
	v_cvt_pk_bf16_f32 v39, v41, v42
	v_pk_add_f32 v[34:35], v[60:61], v[42:43]
	v_exp_f32_e32 v43, v46
	v_pk_add_f32 v[44:45], v[34:35], v[34:35] op_sel_hi:[0,1]
	v_exp_f32_e32 v61, v62
	v_exp_f32_e32 v44, v47
	v_exp_f32_e32 v62, v63
	v_cvt_pk_bf16_f32 v42, v187, v50
	v_add_f32_e32 v63, v61, v43
	v_cvt_pk_bf16_f32 v40, v43, v44
	v_pk_add_f32 v[34:35], v[62:63], v[44:45]
	v_exp_f32_e32 v45, v48
	v_pk_add_f32 v[46:47], v[34:35], v[34:35] op_sel_hi:[0,1]
	v_exp_f32_e32 v63, v64
	v_exp_f32_e32 v46, v49
	v_exp_f32_e32 v64, v65
	v_cvt_pk_bf16_f32 v43, v188, v52
	v_add_f32_e32 v65, v63, v45
	v_cvt_pk_bf16_f32 v41, v45, v46
	v_pk_add_f32 v[34:35], v[64:65], v[46:47]
	v_cvt_pk_bf16_f32 v44, v101, v54
	v_add_f32_e32 v65, v34, v35
	v_cvt_pk_bf16_f32 v35, v51, v100
	v_cvt_pk_bf16_f32 v34, v186, v98
	v_cvt_pk_bf16_f32 v45, v55, v56
	v_cvt_pk_bf16_f32 v54, v57, v58
	v_cvt_pk_bf16_f32 v55, v59, v60
	v_cvt_pk_bf16_f32 v56, v61, v62
	v_cvt_pk_bf16_f32 v57, v63, v64
	s_waitcnt lgkmcnt(0)
	v_mfma_f32_32x32x16_bf16 v[18:33], v[122:125], v[34:37], v[18:33]
	v_mfma_f32_32x32x16_bf16 v[2:17], v[118:121], v[34:37], v[2:17]
	v_mfma_f32_32x32x16_bf16 v[18:33], v[210:213], v[38:41], v[18:33]
	v_mfma_f32_32x32x16_bf16 v[2:17], v[214:217], v[38:41], v[2:17]
	v_mfma_f32_32x32x16_bf16 v[18:33], v[218:221], v[42:45], v[18:33]
	v_mfma_f32_32x32x16_bf16 v[2:17], v[222:225], v[42:45], v[2:17]
	v_mfma_f32_32x32x16_bf16 v[18:33], v[226:229], v[54:57], v[18:33]
	v_mfma_f32_32x32x16_bf16 v[2:17], v[230:233], v[54:57], v[2:17]
	v_add_f32_e32 v183, v183, v65
	s_mov_b64 s[96:97], 0

.LBB2_83:
	ds_read_b64_tr_b16 v[210:211], v178 offset:60416
	ds_read_b64_tr_b16 v[212:213], v178 offset:62976
	ds_read_b64_tr_b16 v[216:217], v178 offset:63040
	ds_read_b64_tr_b16 v[214:215], v178 offset:60480
	ds_read_b64_tr_b16 v[218:219], v181 offset:10240
	ds_read_b64_tr_b16 v[220:221], v181 offset:12800
	ds_read_b64_tr_b16 v[224:225], v181 offset:12864
	ds_read_b64_tr_b16 v[222:223], v181 offset:10304
	ds_read_b64_tr_b16 v[226:227], v181 offset:15360
	ds_read_b64_tr_b16 v[228:229], v181 offset:17920
	ds_read_b64_tr_b16 v[232:233], v181 offset:17984
	ds_read_b64_tr_b16 v[230:231], v181 offset:15424
	v_exp_f32_e32 v186, v34
	v_exp_f32_e32 v187, v50
	v_exp_f32_e32 v98, v35
	v_exp_f32_e32 v50, v51
	v_exp_f32_e32 v188, v52
	v_add_f32_e32 v51, v187, v186
	v_exp_f32_e32 v52, v53
	v_pk_add_f32 v[34:35], v[50:51], v[98:99]
	v_exp_f32_e32 v51, v36
	v_pk_add_f32 v[100:101], v[34:35], v[34:35] op_sel_hi:[0,1]
	v_exp_f32_e32 v100, v37
	v_add_f32_e32 v53, v188, v51
	v_pk_add_f32 v[34:35], v[52:53], v[100:101]
	s_nop 0
	v_pk_add_f32 v[36:37], v[34:35], v[34:35] op_sel_hi:[0,1]
	v_exp_f32_e32 v53, v38
	v_exp_f32_e32 v101, v54
	v_exp_f32_e32 v36, v39
	v_exp_f32_e32 v54, v55
	v_add_f32_e32 v55, v101, v53
	v_pk_add_f32 v[34:35], v[54:55], v[36:37]
	s_nop 0
	v_pk_add_f32 v[38:39], v[34:35], v[34:35] op_sel_hi:[0,1]
	v_exp_f32_e32 v37, v40
	v_exp_f32_e32 v55, v56
	v_exp_f32_e32 v38, v41
	v_exp_f32_e32 v56, v57
	v_cvt_pk_bf16_f32 v36, v53, v36
	v_add_f32_e32 v57, v55, v37
	v_cvt_pk_bf16_f32 v37, v37, v38
	v_pk_add_f32 v[34:35], v[56:57], v[38:39]
	v_exp_f32_e32 v39, v42
	v_pk_add_f32 v[40:41], v[34:35], v[34:35] op_sel_hi:[0,1]
	v_exp_f32_e32 v57, v58
	v_exp_f32_e32 v40, v43
	v_exp_f32_e32 v58, v59
	v_add_f32_e32 v59, v57, v39
	v_cvt_pk_bf16_f32 v38, v39, v40
	v_pk_add_f32 v[34:35], v[58:59], v[40:41]
	v_exp_f32_e32 v41, v44
	v_pk_add_f32 v[42:43], v[34:35], v[34:35] op_sel_hi:[0,1]
	v_exp_f32_e32 v59, v60
	v_exp_f32_e32 v42, v45
	v_exp_f32_e32 v60, v61
	v_add_f32_e32 v61, v59, v41
	v_cvt_pk_bf16_f32 v39, v41, v42
	v_pk_add_f32 v[34:35], v[60:61], v[42:43]
	v_exp_f32_e32 v43, v46
	v_pk_add_f32 v[44:45], v[34:35], v[34:35] op_sel_hi:[0,1]
	v_exp_f32_e32 v61, v62
	v_exp_f32_e32 v44, v47
	v_exp_f32_e32 v62, v63
	v_cvt_pk_bf16_f32 v42, v187, v50
	v_add_f32_e32 v63, v61, v43
	v_cvt_pk_bf16_f32 v40, v43, v44
	v_pk_add_f32 v[34:35], v[62:63], v[44:45]
	v_exp_f32_e32 v45, v48
	v_pk_add_f32 v[46:47], v[34:35], v[34:35] op_sel_hi:[0,1]
	v_exp_f32_e32 v63, v64
	v_exp_f32_e32 v46, v49
	v_exp_f32_e32 v64, v65
	v_cvt_pk_bf16_f32 v43, v188, v52
	v_add_f32_e32 v65, v63, v45
	v_cvt_pk_bf16_f32 v41, v45, v46
	v_pk_add_f32 v[34:35], v[64:65], v[46:47]
	v_cvt_pk_bf16_f32 v44, v101, v54
	v_add_f32_e32 v65, v34, v35
	v_cvt_pk_bf16_f32 v35, v51, v100
	v_cvt_pk_bf16_f32 v34, v186, v98
	v_cvt_pk_bf16_f32 v45, v55, v56
	v_cvt_pk_bf16_f32 v54, v57, v58
	v_cvt_pk_bf16_f32 v55, v59, v60
	v_cvt_pk_bf16_f32 v56, v61, v62
	v_cvt_pk_bf16_f32 v57, v63, v64
	s_waitcnt lgkmcnt(0)
	v_mfma_f32_32x32x16_bf16 v[18:33], v[122:125], v[34:37], v[18:33]
	v_mfma_f32_32x32x16_bf16 v[2:17], v[118:121], v[34:37], v[2:17]
	v_mfma_f32_32x32x16_bf16 v[18:33], v[210:213], v[38:41], v[18:33]
	v_mfma_f32_32x32x16_bf16 v[2:17], v[214:217], v[38:41], v[2:17]
	v_mfma_f32_32x32x16_bf16 v[18:33], v[218:221], v[42:45], v[18:33]
	v_mfma_f32_32x32x16_bf16 v[2:17], v[222:225], v[42:45], v[2:17]
	v_mfma_f32_32x32x16_bf16 v[18:33], v[226:229], v[54:57], v[18:33]
	v_mfma_f32_32x32x16_bf16 v[2:17], v[230:233], v[54:57], v[2:17]
	v_add_f32_e32 v183, v183, v65
	s_mov_b64 s[96:97], 0
